# GLA kdec phase: half of the workgroups (bit 3 of blockIdx.x) start ~10K cycles late so their compute overlaps the other half's load/store bursts
# speedup vs baseline: 1.0035x; 1.0006x over previous
; __device__ __forceinline__ void phase_gla_kdec(Frame& F) {
;     ...
;     for (int unit = F.bid; unit < NB * (SEQ / CH); unit += F.G) {
.LBB0_813:
	s_and_b32 s0, s92, 0x80
	s_mov_b32 s1, 0
	v_cndmask_b32_e64 v0, 0, 1, s[72:73]
	s_cmp_eq_u64 s[0:1], 0
	v_cmp_ne_u32_e64 s[8:9], 1, v0
	s_barrier
	s_cbranch_scc1 .LBB0_822
	s_bitcmp1_b32 s2, 3
	s_cbranch_scc0 .Lsp_813
	s_sleep 127
	s_sleep 33
; #define LAS __attribute__((address_space(3)))
; __device__ __forceinline__ void phase_gla_kdec(Frame& F) {
;     const bf16_t* QKVR = (const bf16_t*)(F.ws + WS_QKVR); const float* w2 = F.in[16]; const float* bg = F.in[17]; const bf16_t* H2 = (const bf16_t*)(F.ws + WS_H2); const bf16_t* WGT = (const bf16_t*)(F.ws + WS_WGT);
;     bf16_t* KVF = (bf16_t*)(F.ws + WS_KVF); float* DEC = (float*)(F.ws + WS_DEC);
;     LAS float* glr = (LAS float*)F.lds;
;     constexpr int KP = QKW + 8, VP = DV + 8;
;     LAS bf16_t* kt = (LAS bf16_t*)(F.lds + 4096);
;     LAS bf16_t* vt = kt + 64 * KP;
;     LAS float* gpart = (LAS float*)(vt + 64 * VP);
;     const int j = F.tid, lane = F.lane, w = F.wave, g = lane >> 4, li = lane & 15, q4 = li >> 2, p4 = li & 3;
;     float w2c[RANK];
; #pragma unroll
;     for (int r = 0; r < RANK; ++r) w2c[r] = w2[r * QKW + j];
;     const float bgc = bg[j];
;     for (int unit = F.bid; unit < NB * (SEQ / CH); unit += F.G) {
;         const size_t m0 = (size_t)unit * CH;
.Lsp_813:
	s_and_b64 vcc, exec, s[8:9]
	s_cbranch_vccnz .LBB0_821
	v_mbcnt_lo_u32_b32 v0, -1, 0
	v_mbcnt_hi_u32_b32 v12, -1, v0
	s_and_b32 s0, s90, 0xffffffc0
	v_add_u32_e32 v0, s0, v12
	v_ashrrev_i32_e32 v1, 31, v0
	v_readlane_b32 s36, v252, 18
	v_lshlrev_b64 v[2:3], 2, v[0:1]
	v_readlane_b32 s37, v252, 19
	v_readlane_b32 s38, v252, 20
	v_readlane_b32 s39, v252, 21
	v_lshl_add_u64 v[4:5], s[36:37], 0, v[2:3]
	v_add_co_u32_e32 v6, vcc, 0x1000, v4
	s_add_u32 s10, s34, 0x4000000
	s_nop 0
	v_addc_co_u32_e32 v7, vcc, 0, v5, vcc
	v_add_co_u32_e32 v8, vcc, 0x2000, v4
	s_addc_u32 s11, s35, 0
	s_nop 0
	v_addc_co_u32_e32 v9, vcc, 0, v5, vcc
	v_add_co_u32_e32 v10, vcc, 0x3000, v4
	s_mov_b64 s[0:1], 0x300000
	s_nop 0
	v_addc_co_u32_e32 v11, vcc, 0, v5, vcc
	v_and_b32_e32 v232, 15, v12
	v_lshrrev_b32_e32 v233, 4, v12
	v_lshlrev_b32_e32 v232, 4, v232
	v_mov_b32_e32 v234, s90
	v_and_b32_e32 v234, 0xffffffc0, v234
	v_lshl_add_u32 v232, v234, 2, v232
	v_lshl_add_u32 v234, v233, 13, v232
	v_add_u32_e32 v235, 0x1000, v234
	global_load_dwordx4 v[16:19], v234, s[36:37]
	global_load_dwordx4 v[20:23], v234, s[36:37] offset:2048
	global_load_dwordx4 v[24:27], v235, s[36:37]
	global_load_dwordx4 v[224:227], v235, s[36:37] offset:2048
	global_load_dwordx4 v[228:231], v232, s[38:39]
	v_add_co_u32_e32 v6, vcc, 0x4000, v4
	s_mov_b32 s13, 0
	s_nop 0
	v_addc_co_u32_e32 v7, vcc, 0, v5, vcc
	v_add_co_u32_e32 v8, vcc, 0x5000, v4
	v_and_b32_e32 v30, 15, v12
	s_nop 0
	v_addc_co_u32_e32 v9, vcc, 0, v5, vcc
	v_add_co_u32_e32 v10, vcc, 0x6000, v4
	v_lshrrev_b32_e32 v1, 4, v12
	s_nop 0
	v_addc_co_u32_e32 v11, vcc, 0, v5, vcc
	v_add_co_u32_e32 v4, vcc, 0x7000, v4
	v_lshlrev_b32_e32 v32, 11, v30
	s_nop 0
	v_addc_co_u32_e32 v5, vcc, 0, v5, vcc
	v_lshl_add_u64 v[4:5], s[38:39], 0, v[2:3]
	v_lshl_add_u64 v[2:3], s[34:35], 0, v[2:3]
	v_lshl_add_u64 v[28:29], v[2:3], 0, s[0:1]
	s_add_u32 s0, s34, 0xe000000
	s_addc_u32 s1, s35, 0
	s_lshl_b32 s12, s3, 1
	s_add_i32 s6, 0, 0x19800
	s_lshl_b64 s[4:5], s[12:13], 12
	v_lshlrev_b32_e32 v4, 3, v1
	v_mov_b32_e32 v33, 0
	s_add_u32 s4, s34, s4
	v_bfe_u32 v6, v12, 2, 2
	v_lshl_or_b32 v7, s3, 7, v4
	v_lshl_add_u64 v[2:3], s[34:35], 0, v[32:33]
	s_addc_u32 s5, s35, s5
	v_lshlrev_b32_e32 v32, 4, v12
	v_or_b32_e32 v9, v4, v6
	v_lshl_add_u64 v[4:5], s[4:5], 0, v[32:33]
	s_mov_b64 s[4:5], 0xa000000
	v_lshlrev_b32_e32 v32, 1, v7
	v_lshl_add_u64 v[34:35], v[4:5], 0, s[4:5]
	v_lshl_add_u64 v[2:3], v[2:3], 0, v[32:33]
	s_mov_b64 s[4:5], 0x2c0000
	v_lshl_add_u64 v[36:37], v[2:3], 0, s[4:5]
	v_add_u32_e32 v2, 64, v32
	v_mov_b32_e32 v3, v33
	v_lshl_add_u64 v[46:47], s[0:1], 0, v[2:3]
	v_add_u32_e32 v2, 0x60, v7
	v_lshl_add_u64 v[38:39], s[0:1], 0, v[32:33]
	v_or_b32_e32 v32, 0x80, v32
	v_ashrrev_i32_e32 v3, 31, v2
	v_lshlrev_b32_e32 v8, 2, v30
	v_lshl_add_u64 v[48:49], s[0:1], 0, v[32:33]
	v_lshl_add_u64 v[50:51], v[2:3], 1, s[0:1]
	v_lshlrev_b32_e32 v2, 8, v1
	s_add_i32 s0, 0, 0x11400
	v_lshlrev_b32_e32 v10, 3, v12
	v_add3_u32 v4, s6, v8, v2
	s_movk_i32 s1, 0x210
	v_mov_b32_e32 v2, s0
	v_mad_u32_u24 v2, v9, s1, v2
	v_and_b32_e32 v3, 24, v10
	s_lshl_b32 s4, s3, 6
	v_add3_u32 v99, v2, v3, s4
	v_ashrrev_i32_e32 v52, 6, v0
	s_movk_i32 s4, 0x410
	v_lshlrev_b32_e32 v7, 4, v0
	v_mul_lo_u32 v5, v52, s4
	v_and_b32_e32 v32, 0x3f0, v7
	v_add3_u32 v101, 0, v5, v32
	v_add_u32_e32 v5, 0x200, v0
	v_ashrrev_i32_e32 v54, 6, v5
	v_mul_lo_u32 v8, v54, s4
	v_add3_u32 v102, 0, v8, v32
	v_add_u32_e32 v8, 0x400, v0
	v_ashrrev_i32_e32 v56, 6, v8
	v_mul_lo_u32 v9, v56, s4
	v_add3_u32 v103, 0, v9, v32
	v_add_u32_e32 v9, 0x600, v0
	v_ashrrev_i32_e32 v58, 6, v9
	v_lshlrev_b32_e32 v2, 3, v0
	v_mul_lo_u32 v11, v58, s4
	v_add3_u32 v104, 0, v11, v32
	v_add_u32_e32 v11, 0x800, v0
	v_ashrrev_i32_e32 v68, 5, v0
	v_ashrrev_i32_e32 v70, 5, v5
	v_and_b32_e32 v2, 0xffffffc0, v2
	v_and_b32_e32 v5, 56, v10
	v_ashrrev_i32_e32 v60, 6, v11
	v_add3_u32 v109, s6, v2, v5
	v_add3_u32 v110, 0, v2, v5
	v_mul_lo_u32 v2, v68, s1
	v_mul_lo_u32 v11, v60, s4
	v_add_u32_e32 v2, s0, v2
	v_and_b32_e32 v5, 0x1c0, v7
	v_add3_u32 v105, 0, v11, v32
	v_add_u32_e32 v11, 0xa00, v0
	v_add3_u32 v111, v2, v5, v3
	v_mul_lo_u32 v2, v70, s1
	v_ashrrev_i32_e32 v62, 6, v11
	v_ashrrev_i32_e32 v72, 5, v8
	v_add_u32_e32 v2, s0, v2
	v_mul_lo_u32 v11, v62, s4
	v_add3_u32 v112, v2, v5, v3
	v_mul_lo_u32 v2, v72, s1
	v_add3_u32 v106, 0, v11, v32
	v_add_u32_e32 v11, 0xc00, v0
	v_ashrrev_i32_e32 v74, 5, v9
	v_add_u32_e32 v2, s0, v2
	v_ashrrev_i32_e32 v64, 6, v11
	v_add3_u32 v113, v2, v5, v3
	v_mul_lo_u32 v2, v74, s1
	v_mul_lo_u32 v11, v64, s4
	v_add_u32_e32 v2, s0, v2
	v_add3_u32 v107, 0, v11, v32
	v_add_u32_e32 v11, 0xe00, v0
	v_add3_u32 v114, v2, v5, v3
	v_mul_u32_u24_e32 v2, 0x410, v6
	s_movk_i32 s0, 0x2080
	s_lshl_b32 s7, s3, 12
	v_ashrrev_i32_e32 v66, 6, v11
	s_lshl_b32 s19, s2, 2
	s_lshl_b32 s20, s33, 2
	v_mad_u32_u24 v1, v1, s0, v2
	s_mul_i32 s0, s2, 0x60000
	v_mul_lo_u32 v11, v66, s4
	v_and_b32_e32 v2, 3, v12
	s_mul_hi_i32 s1, s2, 0x60000
	s_add_u32 s0, s34, s0
	v_lshl_add_u32 v97, v0, 1, 0
	v_add3_u32 v108, 0, v11, v32
	v_lshl_add_u64 v[76:77], s[10:11], 0, v[32:33]
	v_and_b32_e32 v32, 0x1f0, v7
	v_lshlrev_b32_e32 v2, 3, v2
	v_and_b32_e32 v0, 31, v0
	s_addc_u32 s1, s35, s1
	v_lshl_add_u64 v[78:79], s[10:11], 0, v[32:33]
	v_add3_u32 v115, v1, v2, 0
	v_lshlrev_b32_e32 v32, 4, v0
	s_movk_i32 s21, 0x1800
	v_mov_b64_e32 v[0:1], s[0:1]
	v_mad_i64_i32 v[2:3], s[0:1], v74, s21, v[0:1]
	s_mov_b64 s[0:1], 0x4000a00
	s_nop 0
	v_lshl_add_u64 v[80:81], v[2:3], 0, s[0:1]
	v_mad_i64_i32 v[2:3], s[4:5], v72, s21, v[0:1]
	v_lshl_add_u64 v[82:83], v[2:3], 0, s[0:1]
	v_mad_i64_i32 v[2:3], s[4:5], v70, s21, v[0:1]
	v_mad_i64_i32 v[0:1], s[4:5], v68, s21, v[0:1]
	s_movk_i32 s18, 0x1000
	v_add_u32_e32 v98, 0x1000, v97
	v_or_b32_e32 v40, 16, v30
	v_or_b32_e32 v42, 32, v30
	v_or_b32_e32 v44, 48, v30
	v_add_u32_e32 v100, 0x4200, v99
	v_ashrrev_i32_e32 v53, 31, v52
	v_ashrrev_i32_e32 v55, 31, v54
	v_ashrrev_i32_e32 v57, 31, v56
	v_ashrrev_i32_e32 v59, 31, v58
	v_ashrrev_i32_e32 v61, 31, v60
	v_ashrrev_i32_e32 v63, 31, v62
	v_ashrrev_i32_e32 v65, 31, v64
	v_ashrrev_i32_e32 v67, 31, v66
	v_ashrrev_i32_e32 v69, 31, v68
	v_ashrrev_i32_e32 v71, 31, v70
	v_ashrrev_i32_e32 v73, 31, v72
	v_ashrrev_i32_e32 v75, 31, v74
	s_mul_hi_i32 s11, s33, 0x60000
	s_mul_i32 s10, s33, 0x60000
	v_lshl_add_u64 v[84:85], v[2:3], 0, s[0:1]
	v_lshl_add_u64 v[86:87], v[0:1], 0, s[0:1]
	v_add_u32_e32 v116, s7, v4
	s_mov_b32 s22, 0xbfb8aa3b
	s_mov_b32 s23, 0x3d800000
	s_movk_i32 s24, 0x7fff
	s_mov_b64 s[12:13], 0x200
	s_mov_b32 s14, s2
	v_readlane_b32 s40, v252, 22
	v_readlane_b32 s41, v252, 23
	v_readlane_b32 s42, v252, 24
	v_readlane_b32 s43, v252, 25
	v_readlane_b32 s44, v252, 26
	v_readlane_b32 s45, v252, 27
	v_readlane_b32 s46, v252, 28
	v_readlane_b32 s47, v252, 29
	v_readlane_b32 s48, v252, 30
	v_readlane_b32 s49, v252, 31
	v_readlane_b32 s50, v252, 32
	v_readlane_b32 s51, v252, 33
	s_branch .LBB0_817
